# adds: G1 copy-out (Q/K and linear kinds) reads one segment ahead - next LDS tile read issued before waiting for the current one, two alternating data quads, counted lgkmcnt
# speedup vs baseline: 1.0083x; 1.0018x over previous
; DI void st_nt16(void* q, uint4 v) { ntu4 t = {v.x, v.y, v.z, v.w}; __builtin_nontemporal_store(t, (ntu4*)q); }
; template <int CT>
; DI void phase_g1(int c, int l) {
;     ...
;       } else if (sd.kind == 1) {
;         const int dsh = sd.dsh, L = S0 >> dsh;
; #pragma unroll
;         for (int i = 0; i < 4; ++i) {
;           const int idx = etid + i * NTHREADS, c8 = idx >> 8, u = idx & 255;
;           const int r = u >> (8 - dsh), j = u & ((256 >> dsh) - 1), tt = r + (j << dsh);
;           const uint4 val = *(const uint4*)(shm + tt * TP + (seg * 64 + c8 * 8) * 2);
;           const int rowg = sl + r * L + (pos0 >> dsh) + j;
;           st_nt16(sd.base + ((((size_t)(rowg >> 5)) * 4 + (c8 >> 1)) * 64 + (c8 & 1) * 32 + (rowg & 31)) * 8, val);
;         }
;       } else {
; #pragma unroll
;         for (int i = 0; i < 4; ++i) {
;           const int idx = etid + i * NTHREADS, tt = idx >> 3, c8 = idx & 7;
;           const uint4 val = *(const uint4*)(shm + tt * TP + (seg * 64 + c8 * 8) * 2);
;           *(uint4*)(sd.base + (size_t)(tbase + tt) * sd.ld + c8 * 8) = val;
;         }
.LBB0_561:
	s_cmp_eq_u32 s74, 1
	s_mov_b64 s[26:27], -1
	s_cbranch_scc1 .LBB0_563
	v_add_u32_e32 v161, s25, v164
	ds_read_b128 v[180:183], v161
	v_add_u32_e32 v161, s25, v162
	ds_read_b128 v[190:193], v161
	v_mul_lo_u32 v161, s9, v142
	v_mul_lo_u32 v163, s8, v7
	v_mad_u64_u32 v[186:187], s[26:27], s8, v142, 0
	v_lshl_add_u64 v[184:185], s[6:7], 0, v[0:1]
	v_add3_u32 v187, v187, v163, v161
	v_lshl_add_u64 v[186:187], v[186:187], 1, v[184:185]
	s_waitcnt lgkmcnt(1)
	global_store_dwordx4 v[186:187], v[180:183], off
	v_add_u32_e32 v161, s25, v160
	ds_read_b128 v[180:183], v161
	v_mul_lo_u32 v161, s9, v144
	v_mul_lo_u32 v163, s8, v15
	v_mad_u64_u32 v[186:187], s[26:27], s8, v144, 0
	v_add3_u32 v187, v187, v163, v161
	v_lshl_add_u64 v[186:187], v[186:187], 1, v[184:185]
	s_waitcnt lgkmcnt(1)
	global_store_dwordx4 v[186:187], v[190:193], off
	v_add_u32_e32 v161, s25, v158
	ds_read_b128 v[190:193], v161
	v_mul_lo_u32 v161, s9, v146
	v_mul_lo_u32 v163, s8, v143
	v_mad_u64_u32 v[186:187], s[26:27], s8, v146, 0
	v_add3_u32 v187, v187, v163, v161
	v_lshl_add_u64 v[186:187], v[186:187], 1, v[184:185]
	s_waitcnt lgkmcnt(1)
	global_store_dwordx4 v[186:187], v[180:183], off
	v_mul_lo_u32 v161, s9, v148
	v_mul_lo_u32 v163, s8, v145
	v_mad_u64_u32 v[186:187], s[8:9], s8, v148, 0
	v_add3_u32 v187, v187, v163, v161
	v_lshl_add_u64 v[184:185], v[186:187], 1, v[184:185]
	s_mov_b64 s[26:27], 0
	s_waitcnt lgkmcnt(0)
	global_store_dwordx4 v[184:185], v[190:193], off
.LBB0_563:
	s_andn2_b64 vcc, exec, s[26:27]
	s_cbranch_vccnz .LBB0_523
	s_sub_i32 s9, 8, s54
	v_lshrrev_b32_sdwa v161, s9, v14 dst_sel:DWORD dst_unused:UNUSED_PAD src0_sel:DWORD src1_sel:BYTE_0
	s_lshr_b32 s9, 0x100, s54
	s_add_i32 s9, s9, -1
	s_lshr_b32 s8, s19, s54
	v_and_b32_sdwa v163, s9, v14 dst_sel:DWORD dst_unused:UNUSED_PAD src0_sel:DWORD src1_sel:BYTE_0
	v_lshl_add_u32 v165, v163, s54, v161
	v_mul_u32_u24_e32 v161, s8, v161
	s_lshr_b32 s8, s22, s54
	s_add_i32 s8, s8, s21
	v_add3_u32 v161, s8, v161, v163
	v_mul_lo_u32 v165, v165, s82
	v_ashrrev_i32_e32 v180, 5, v161
	v_ashrrev_i32_e32 v181, 31, v180
	v_add3_u32 v163, v147, v165, s25
	v_lshlrev_b64 v[184:185], 8, v[180:181]
	ds_read_b128 v[180:183], v163
	v_add3_u32 v163, v149, v165, s25
	ds_read_b128 v[190:193], v163
	v_and_b32_e32 v161, 31, v161
	v_lshl_add_u64 v[186:187], v[8:9], 0, v[184:185]
	v_or_b32_e32 v186, v186, v161
	v_lshl_add_u64 v[186:187], v[186:187], 4, s[6:7]
	s_waitcnt lgkmcnt(1)
	global_store_dwordx4 v[186:187], v[180:183], off nt
	v_add3_u32 v163, v166, v165, s25
	ds_read_b128 v[180:183], v163
	v_lshl_add_u64 v[186:187], v[10:11], 0, v[184:185]
	v_or_b32_e32 v186, v186, v161
	v_lshl_add_u64 v[186:187], v[186:187], 4, s[6:7]
	s_waitcnt lgkmcnt(1)
	global_store_dwordx4 v[186:187], v[190:193], off nt
	v_add3_u32 v163, v167, v165, s25
	ds_read_b128 v[190:193], v163
	v_lshl_add_u64 v[186:187], v[12:13], 0, v[184:185]
	v_or_b32_e32 v186, v186, v161
	v_lshl_add_u64 v[186:187], v[186:187], 4, s[6:7]
	s_waitcnt lgkmcnt(1)
	global_store_dwordx4 v[186:187], v[180:183], off nt
	v_lshl_add_u64 v[184:185], v[16:17], 0, v[184:185]
	v_or_b32_e32 v184, v184, v161
	v_lshl_add_u64 v[184:185], v[184:185], 4, s[6:7]
	s_waitcnt lgkmcnt(0)
	global_store_dwordx4 v[184:185], v[190:193], off nt
	s_branch .LBB0_523
